# attention loops: last QK MFMA, P0 packing and V address setup issued before the mid barrier (register-only work moved from the followers' critical PV phase to the QK phase)
# speedup vs baseline: 1.0421x; 1.0040x over previous
.LBB0_226:
	s_lshl_b32 s86, s33, 15
	v_or_b32_e32 v102, s86, v200
	s_waitcnt lgkmcnt(0)
	s_barrier
	v_add_u32_e32 v129, v102, v202
	v_add_u32_e32 v151, v102, v203
	v_add_u32_e32 v157, v102, v204
	v_add_u32_e32 v161, v102, v205
	ds_read_b128 v[98:101], v129
	ds_read_b128 v[252:255], v151
	v_add_f32_e32 v232, s74, v162
	v_add_f32_e32 v233, s75, v162
	v_add_f32_e32 v234, s64, v162
	v_add_f32_e32 v235, s65, v162
	v_add_f32_e32 v236, s58, v162
	v_add_f32_e32 v237, s59, v162
	v_add_f32_e32 v238, s56, v162
	v_add_f32_e32 v239, s57, v162
	s_waitcnt vmcnt(3) lgkmcnt(1)
	v_mfma_f32_32x32x16_bf16 v[216:231], v[98:101], v[82:85], v[216:231]
	ds_read_b128 v[98:101], v157
	s_add_i32 s6, s33, 1
	v_add_u32_e32 v128, 1, v128
	s_cmp_lg_u32 s33, 2
	v_cmp_ge_i32_e32 vcc, v128, v155
	v_add_f32_e32 v240, s54, v162
	v_add_f32_e32 v241, s55, v162
	v_add_f32_e32 v242, s48, v162
	v_add_f32_e32 v243, s49, v162
	s_waitcnt vmcnt(2) lgkmcnt(1)
	v_mfma_f32_32x32x16_bf16 v[216:231], v[252:255], v[86:89], v[216:231]
	ds_read_b128 v[252:255], v161
	s_cselect_b32 s33, s6, 0
	v_add_u32_e32 v127, 64, v127
	s_or_b64 s[84:85], vcc, s[84:85]
	v_add_f32_e32 v244, s34, v162
	v_add_f32_e32 v245, s35, v162
	v_add_f32_e32 v246, s30, v162
	v_add_f32_e32 v247, s31, v162
	v_fma_f32 v232, v106, |v232|, v146
	v_fma_f32 v233, v106, |v233|, v146
	s_waitcnt vmcnt(1) lgkmcnt(1)
	v_mfma_f32_32x32x16_bf16 v[216:231], v[98:101], v[90:93], v[216:231]
	ds_read_b128 v[162:165], v129 offset:8192
	v_fma_f32 v234, v106, |v234|, v146
	v_fma_f32 v235, v106, |v235|, v146
	v_fma_f32 v236, v106, |v236|, v146
	v_fma_f32 v237, v106, |v237|, v146
	v_fma_f32 v238, v106, |v238|, v146
	v_fma_f32 v239, v106, |v239|, v146
	s_waitcnt vmcnt(0) lgkmcnt(1)
	v_mfma_f32_32x32x16_bf16 v[216:231], v[252:255], v[94:97], v[216:231]
	ds_read_b128 v[252:255], v151 offset:8192
	v_fma_f32 v240, v106, |v240|, v146
	v_fma_f32 v241, v106, |v241|, v146
	v_fma_f32 v242, v106, |v242|, v146
	v_fma_f32 v243, v106, |v243|, v146
	v_fma_f32 v244, v106, |v244|, v146
	v_fma_f32 v245, v106, |v245|, v146
	v_fma_f32 v246, v106, |v246|, v146
	v_fma_f32 v247, v106, |v247|, v146
	s_nop 2
	v_exp_f32_e32 v66, v216
	v_exp_f32_e32 v166, v217
	v_exp_f32_e32 v168, v218
	v_exp_f32_e32 v170, v219
	v_add_f32_e32 v132, 0, v66
	s_waitcnt lgkmcnt(1)
	v_mfma_f32_32x32x16_bf16 v[232:247], v[162:165], v[82:85], v[232:247]
	ds_read_b128 v[162:165], v157 offset:8192
	v_exp_f32_e32 v188, v228
	v_exp_f32_e32 v212, v229
	v_exp_f32_e32 v214, v230
	v_exp_f32_e32 v250, v231
	v_cvt_pk_bf16_f32 v98, v66, v166
	s_waitcnt lgkmcnt(1)
	v_mfma_f32_32x32x16_bf16 v[232:247], v[252:255], v[86:89], v[232:247]
	ds_read_b128 v[252:255], v161 offset:8192
	v_exp_f32_e32 v172, v220
	v_exp_f32_e32 v174, v221
	v_exp_f32_e32 v176, v222
	v_exp_f32_e32 v178, v223
	s_waitcnt lgkmcnt(1)
	v_mfma_f32_32x32x16_bf16 v[232:247], v[162:165], v[90:93], v[232:247]
	v_exp_f32_e32 v180, v224
	v_exp_f32_e32 v182, v225
	v_exp_f32_e32 v184, v226
	v_exp_f32_e32 v186, v227
	s_waitcnt lgkmcnt(0)
	v_mfma_f32_32x32x16_bf16 v[232:247], v[252:255], v[94:97], v[232:247]
	v_cvt_pk_bf16_f32 v99, v168, v170
	v_cvt_pk_bf16_f32 v100, v172, v174
	v_cvt_pk_bf16_f32 v101, v176, v178
	v_cvt_pk_bf16_f32 v102, v180, v182
	v_cvt_pk_bf16_f32 v103, v184, v186
	v_cvt_pk_bf16_f32 v104, v188, v212
	v_cvt_pk_bf16_f32 v105, v214, v250
	v_or_b32_e32 v80, s86, v193
	v_add_u32_e32 v81, v80, v195
	v_add_u32_e32 v129, v80, v196
	s_barrier
	ds_read_b128 v[74:77], v81 offset:16384
	s_nop 0
	v_exp_f32_e32 v251, v246
	v_exp_f32_e32 v161, v247
	v_exp_f32_e32 v183, v240
	v_exp_f32_e32 v185, v241
	v_exp_f32_e32 v187, v242
	v_exp_f32_e32 v189, v243
	ds_read_b128 v[252:255], v129 offset:16384
	s_waitcnt lgkmcnt(1)
	v_mfma_f32_32x32x16_bf16 v[50:65], v[74:77], v[98:101], v[50:65]
	ds_read_b128 v[74:77], v81 offset:20480
	v_exp_f32_e32 v167, v232
	v_exp_f32_e32 v169, v233
	v_exp_f32_e32 v171, v234
	v_exp_f32_e32 v173, v235
	v_pk_add_f32 v[66:67], v[166:167], v[132:133]
	v_exp_f32_e32 v175, v236
	s_waitcnt lgkmcnt(1)
	v_mfma_f32_32x32x16_bf16 v[50:65], v[252:255], v[102:105], v[50:65]
	ds_read_b128 v[252:255], v129 offset:20480
	v_add_f32_e64 v66, v168, v66
	v_add_f32_e64 v67, v169, v67
	v_exp_f32_e32 v177, v237
	v_pk_add_f32 v[66:67], v[170:171], v[66:67]
	v_exp_f32_e32 v179, v238
	v_pk_add_f32 v[66:67], v[172:173], v[66:67]
	v_exp_f32_e32 v181, v239
	s_waitcnt lgkmcnt(1)
	v_mfma_f32_32x32x16_bf16 v[34:49], v[74:77], v[98:101], v[34:49]
	ds_read_b128 v[74:77], v81 offset:24576
	v_add_f32_e64 v66, v174, v66
	v_add_f32_e64 v67, v175, v67
	v_exp_f32_e32 v213, v244
	v_pk_add_f32 v[66:67], v[176:177], v[66:67]
	v_exp_f32_e32 v215, v245
	v_pk_add_f32 v[66:67], v[178:179], v[66:67]
	v_cvt_pk_bf16_f32 v68, v175, v177
	s_waitcnt lgkmcnt(1)
	v_mfma_f32_32x32x16_bf16 v[34:49], v[252:255], v[102:105], v[34:49]
	ds_read_b128 v[252:255], v129 offset:24576
	v_add_f32_e64 v66, v180, v66
	v_add_f32_e64 v67, v181, v67
	v_cvt_pk_bf16_f32 v69, v179, v181
	v_add_f32_e64 v66, v182, v66
	v_add_f32_e64 v67, v183, v67
	v_cvt_pk_bf16_f32 v70, v183, v185
	v_pk_add_f32 v[66:67], v[184:185], v[66:67]
	v_cvt_pk_bf16_f32 v71, v187, v189
	s_waitcnt lgkmcnt(1)
	v_mfma_f32_32x32x16_bf16 v[18:33], v[74:77], v[98:101], v[18:33]
	ds_read_b128 v[74:77], v81 offset:28672
	v_add_f32_e64 v66, v186, v66
	v_add_f32_e64 v67, v187, v67
	v_cvt_pk_bf16_f32 v72, v213, v215
	v_add_f32_e64 v66, v188, v66
	v_add_f32_e64 v67, v189, v67
	v_cvt_pk_bf16_f32 v73, v251, v161
	v_pk_add_f32 v[66:67], v[212:213], v[66:67]
	s_waitcnt lgkmcnt(1)
	v_mfma_f32_32x32x16_bf16 v[18:33], v[252:255], v[102:105], v[18:33]
	ds_read_b128 v[252:255], v129 offset:28672
	v_add_u32_e32 v81, v80, v197
	v_add_f32_e64 v66, v214, v66
	v_add_f32_e64 v67, v215, v67
	v_add_u32_e32 v80, v80, v198
	v_pk_add_f32 v[66:67], v[250:251], v[66:67]
	s_nop 0
	v_pk_add_f32 v[78:79], v[160:161], v[66:67]
	s_waitcnt lgkmcnt(1)
	v_mfma_f32_32x32x16_bf16 v[2:17], v[74:77], v[98:101], v[2:17]
	ds_read_b128 v[74:77], v81 offset:16384
	v_cvt_pk_bf16_f32 v66, v167, v169
	v_cvt_pk_bf16_f32 v67, v171, v173
	v_add_f32_e32 v160, v78, v79
	s_waitcnt lgkmcnt(1)
	v_mfma_f32_32x32x16_bf16 v[2:17], v[252:255], v[102:105], v[2:17]
	ds_read_b128 v[252:255], v80 offset:16384
	v_cvt_f32_i32_e32 v162, v127
	v_add_f32_e32 v217, 1.0, v162
	v_add_f32_e32 v218, s12, v162
	v_add_f32_e32 v219, s13, v162
	s_waitcnt lgkmcnt(1)
	v_mfma_f32_32x32x16_bf16 v[50:65], v[74:77], v[66:69], v[50:65]
	ds_read_b128 v[74:77], v81 offset:20480
	v_add_f32_e32 v220, s16, v162
	v_add_f32_e32 v221, s17, v162
	v_add_f32_e32 v222, s18, v162
	v_add_f32_e32 v223, s19, v162
	s_waitcnt lgkmcnt(1)
	v_mfma_f32_32x32x16_bf16 v[50:65], v[252:255], v[70:73], v[50:65]
	ds_read_b128 v[252:255], v80 offset:20480
	v_add_f32_e32 v224, s20, v162
	v_add_f32_e32 v225, s21, v162
	v_add_f32_e32 v226, s22, v162
	v_add_f32_e32 v227, s23, v162
	s_waitcnt lgkmcnt(1)
	v_mfma_f32_32x32x16_bf16 v[34:49], v[74:77], v[66:69], v[34:49]
	ds_read_b128 v[74:77], v81 offset:24576
	v_add_f32_e32 v228, s26, v162
	v_add_f32_e32 v229, s27, v162
	v_add_f32_e32 v230, s28, v162
	v_add_f32_e32 v231, s29, v162
	s_waitcnt lgkmcnt(1)
	v_mfma_f32_32x32x16_bf16 v[34:49], v[252:255], v[70:73], v[34:49]
	ds_read_b128 v[252:255], v80 offset:24576
	v_fma_f32 v216, v106, |v162|, v146
	v_fma_f32 v217, v106, |v217|, v146
	v_fma_f32 v218, v106, |v218|, v146
	v_fma_f32 v219, v106, |v219|, v146
	s_waitcnt lgkmcnt(1)
	v_mfma_f32_32x32x16_bf16 v[18:33], v[74:77], v[66:69], v[18:33]
	ds_read_b128 v[74:77], v81 offset:28672
	v_fma_f32 v220, v106, |v220|, v146
	v_fma_f32 v221, v106, |v221|, v146
	v_fma_f32 v222, v106, |v222|, v146
	v_fma_f32 v223, v106, |v223|, v146
	s_waitcnt lgkmcnt(1)
	v_mfma_f32_32x32x16_bf16 v[18:33], v[252:255], v[70:73], v[18:33]
	ds_read_b128 v[252:255], v80 offset:28672
	v_fma_f32 v224, v106, |v224|, v146
	v_fma_f32 v225, v106, |v225|, v146
	v_fma_f32 v226, v106, |v226|, v146
	v_fma_f32 v227, v106, |v227|, v146
	s_waitcnt lgkmcnt(1)
	v_mfma_f32_32x32x16_bf16 v[2:17], v[74:77], v[66:69], v[2:17]
	v_fma_f32 v228, v106, |v228|, v146
	v_fma_f32 v229, v106, |v229|, v146
	v_fma_f32 v230, v106, |v230|, v146
	v_fma_f32 v231, v106, |v231|, v146
	s_waitcnt lgkmcnt(0)
	v_mfma_f32_32x32x16_bf16 v[2:17], v[252:255], v[70:73], v[2:17]
	s_andn2_b64 exec, exec, s[84:85]
	s_cbranch_execnz .LBB0_226
	s_or_b64 exec, exec, s[84:85]

.LBB0_232:
	s_or_b64 exec, exec, s[86:87]
	s_and_b64 s[6:7], exec, vcc
	s_or_b64 s[84:85], s[6:7], s[84:85]
	s_lshl_b32 s86, s90, 15
	v_or_b32_e32 v102, s86, v200
	v_add_u32_e32 v127, v102, v202
	v_add_u32_e32 v129, v102, v203
	v_add_u32_e32 v157, v102, v204
	v_add_u32_e32 v161, v102, v205
	ds_read_b128 v[98:101], v127
	ds_read_b128 v[252:255], v129
	v_add_f32_e32 v232, s74, v212
	v_add_f32_e32 v233, s75, v212
	v_add_f32_e32 v234, s64, v212
	v_add_f32_e32 v235, s65, v212
	v_add_f32_e32 v236, s58, v212
	v_add_f32_e32 v237, s59, v212
	v_add_f32_e32 v238, s56, v212
	v_add_f32_e32 v239, s57, v212
	s_waitcnt lgkmcnt(1)
	v_mfma_f32_32x32x16_bf16 v[216:231], v[98:101], v[82:85], v[216:231]
	ds_read_b128 v[98:101], v157
	v_add_u32_e32 v141, 1, v141
	s_mov_b32 s90, s33
	v_add_f32_e32 v240, s54, v212
	v_add_f32_e32 v241, s55, v212
	v_add_f32_e32 v242, s48, v212
	v_add_f32_e32 v243, s49, v212
	s_waitcnt lgkmcnt(1)
	v_mfma_f32_32x32x16_bf16 v[216:231], v[252:255], v[86:89], v[216:231]
	ds_read_b128 v[252:255], v161
	v_add_f32_e32 v244, s34, v212
	v_add_f32_e32 v245, s35, v212
	v_add_f32_e32 v246, s30, v212
	v_add_f32_e32 v247, s31, v212
	v_fma_f32 v232, v110, |v232|, v146
	v_fma_f32 v233, v110, |v233|, v146
	s_waitcnt lgkmcnt(1)
	v_mfma_f32_32x32x16_bf16 v[216:231], v[98:101], v[90:93], v[216:231]
	ds_read_b128 v[212:215], v127 offset:8192
	v_fma_f32 v234, v110, |v234|, v146
	v_fma_f32 v235, v110, |v235|, v146
	v_fma_f32 v236, v110, |v236|, v146
	v_fma_f32 v237, v110, |v237|, v146
	v_fma_f32 v238, v110, |v238|, v146
	v_fma_f32 v239, v110, |v239|, v146
	s_waitcnt lgkmcnt(1)
	v_mfma_f32_32x32x16_bf16 v[216:231], v[252:255], v[94:97], v[216:231]
	ds_read_b128 v[252:255], v129 offset:8192
	v_fma_f32 v240, v110, |v240|, v146
	v_fma_f32 v241, v110, |v241|, v146
	v_fma_f32 v242, v110, |v242|, v146
	v_fma_f32 v243, v110, |v243|, v146
	v_fma_f32 v244, v110, |v244|, v146
	v_fma_f32 v245, v110, |v245|, v146
	v_fma_f32 v246, v110, |v246|, v146
	v_fma_f32 v247, v110, |v247|, v146
	s_nop 2
	v_exp_f32_e32 v66, v216
	v_exp_f32_e32 v128, v217
	v_exp_f32_e32 v164, v218
	v_exp_f32_e32 v162, v219
	v_add_f32_e32 v132, 0, v66
	s_waitcnt lgkmcnt(1)
	v_mfma_f32_32x32x16_bf16 v[232:247], v[212:215], v[82:85], v[232:247]
	ds_read_b128 v[212:215], v157 offset:8192
	v_exp_f32_e32 v184, v228
	v_exp_f32_e32 v182, v229
	v_exp_f32_e32 v188, v230
	v_exp_f32_e32 v186, v231
	v_cvt_pk_bf16_f32 v102, v66, v128
	s_waitcnt lgkmcnt(1)
	v_mfma_f32_32x32x16_bf16 v[232:247], v[252:255], v[86:89], v[232:247]
	ds_read_b128 v[252:255], v161 offset:8192
	v_exp_f32_e32 v168, v220
	v_exp_f32_e32 v166, v221
	v_exp_f32_e32 v172, v222
	v_exp_f32_e32 v170, v223
	s_waitcnt lgkmcnt(1)
	v_mfma_f32_32x32x16_bf16 v[232:247], v[212:215], v[90:93], v[232:247]
	v_exp_f32_e32 v176, v224
	v_exp_f32_e32 v174, v225
	v_exp_f32_e32 v180, v226
	v_exp_f32_e32 v178, v227
	s_waitcnt lgkmcnt(0)
	v_mfma_f32_32x32x16_bf16 v[232:247], v[252:255], v[94:97], v[232:247]
	v_cvt_pk_bf16_f32 v103, v164, v162
	v_cvt_pk_bf16_f32 v104, v168, v166
	v_cvt_pk_bf16_f32 v105, v172, v170
	v_cvt_pk_bf16_f32 v98, v176, v174
	v_cvt_pk_bf16_f32 v99, v180, v178
	v_cvt_pk_bf16_f32 v100, v184, v182
	v_cvt_pk_bf16_f32 v101, v188, v186
	v_or_b32_e32 v80, s86, v193
	v_add_u32_e32 v81, v80, v195
	v_add_u32_e32 v127, v80, v196
	s_barrier
	ds_read_b128 v[76:79], v81 offset:16384
	s_nop 0
	v_exp_f32_e32 v187, v246
	v_exp_f32_e32 v161, v247
	v_exp_f32_e32 v179, v242
	v_exp_f32_e32 v185, v243
	v_exp_f32_e32 v183, v244
	v_exp_f32_e32 v189, v245
	ds_read_b128 v[252:255], v127 offset:16384
	s_waitcnt lgkmcnt(1)
	v_mfma_f32_32x32x16_bf16 v[50:65], v[76:79], v[102:105], v[50:65]
	ds_read_b128 v[76:79], v81 offset:20480
	v_exp_f32_e32 v129, v232
	v_exp_f32_e32 v165, v233
	v_exp_f32_e32 v163, v234
	v_exp_f32_e32 v169, v235
	v_pk_add_f32 v[66:67], v[128:129], v[132:133]
	v_exp_f32_e32 v167, v236
	s_waitcnt lgkmcnt(1)
	v_mfma_f32_32x32x16_bf16 v[50:65], v[252:255], v[98:101], v[50:65]
	ds_read_b128 v[252:255], v127 offset:20480
	v_add_f32_e64 v66, v164, v66
	v_add_f32_e64 v67, v165, v67
	v_exp_f32_e32 v173, v237
	v_pk_add_f32 v[66:67], v[162:163], v[66:67]
	v_exp_f32_e32 v171, v238
	v_exp_f32_e32 v177, v239
	v_pk_add_f32 v[66:67], v[168:169], v[66:67]
	s_waitcnt lgkmcnt(1)
	v_mfma_f32_32x32x16_bf16 v[34:49], v[76:79], v[102:105], v[34:49]
	ds_read_b128 v[76:79], v81 offset:24576
	v_exp_f32_e32 v175, v240
	v_pk_add_f32 v[66:67], v[166:167], v[66:67]
	v_exp_f32_e32 v181, v241
	v_pk_add_f32 v[66:67], v[172:173], v[66:67]
	v_cvt_pk_bf16_f32 v70, v129, v165
	v_pk_add_f32 v[66:67], v[170:171], v[66:67]
	s_waitcnt lgkmcnt(1)
	v_mfma_f32_32x32x16_bf16 v[34:49], v[252:255], v[98:101], v[34:49]
	ds_read_b128 v[252:255], v127 offset:24576
	v_cvt_pk_bf16_f32 v71, v163, v169
	v_cvt_pk_bf16_f32 v72, v167, v173
	v_cvt_pk_bf16_f32 v73, v171, v177
	v_add_f32_e64 v66, v176, v66
	v_add_f32_e64 v67, v177, v67
	v_cvt_pk_bf16_f32 v68, v183, v189
	v_pk_add_f32 v[66:67], v[174:175], v[66:67]
	s_waitcnt lgkmcnt(1)
	v_mfma_f32_32x32x16_bf16 v[18:33], v[76:79], v[102:105], v[18:33]
	ds_read_b128 v[76:79], v81 offset:28672
	v_add_f32_e64 v66, v180, v66
	v_add_f32_e64 v67, v181, v67
	v_cvt_pk_bf16_f32 v69, v187, v161
	v_add_f32_e64 v66, v178, v66
	v_add_f32_e64 v67, v179, v67
	v_pk_add_f32 v[66:67], v[184:185], v[66:67]
	s_waitcnt lgkmcnt(1)
	v_mfma_f32_32x32x16_bf16 v[18:33], v[252:255], v[98:101], v[18:33]
	ds_read_b128 v[252:255], v127 offset:28672
	v_add_u32_e32 v81, v80, v197
	v_add_u32_e32 v80, v80, v198
	v_add_f32_e64 v66, v182, v66
	v_add_f32_e64 v67, v183, v67
	v_pk_add_f32 v[66:67], v[188:189], v[66:67]
	s_waitcnt lgkmcnt(1)
	v_mfma_f32_32x32x16_bf16 v[2:17], v[76:79], v[102:105], v[2:17]
	ds_read_b128 v[76:79], v81 offset:16384
	v_add_f32_e64 v66, v186, v66
	v_add_f32_e64 v67, v187, v67
	v_add_f32_e64 v74, v160, v66
	v_add_f32_e64 v75, v161, v67
	v_cvt_pk_bf16_f32 v66, v175, v181
	v_cvt_pk_bf16_f32 v67, v179, v185
	v_add_f32_e32 v160, v74, v75
	s_waitcnt lgkmcnt(1)
	v_mfma_f32_32x32x16_bf16 v[2:17], v[252:255], v[98:101], v[2:17]
	ds_read_b128 v[252:255], v80 offset:16384
	v_add_u32_e32 v250, v151, v126
	v_cvt_f32_i32_e32 v212, v250
	v_add_f32_e32 v217, 1.0, v212
	v_add_f32_e32 v218, s12, v212
	v_add_f32_e32 v219, s13, v212
	s_waitcnt lgkmcnt(1)
	v_mfma_f32_32x32x16_bf16 v[50:65], v[76:79], v[70:73], v[50:65]
	ds_read_b128 v[76:79], v81 offset:20480
	v_add_f32_e32 v220, s16, v212
	v_add_f32_e32 v221, s17, v212
	v_add_f32_e32 v222, s18, v212
	v_add_f32_e32 v223, s19, v212
	s_waitcnt lgkmcnt(1)
	v_mfma_f32_32x32x16_bf16 v[50:65], v[252:255], v[66:69], v[50:65]
	ds_read_b128 v[252:255], v80 offset:20480
	v_add_f32_e32 v224, s20, v212
	v_add_f32_e32 v225, s21, v212
	v_add_f32_e32 v226, s22, v212
	v_add_f32_e32 v227, s23, v212
	s_waitcnt lgkmcnt(1)
	v_mfma_f32_32x32x16_bf16 v[34:49], v[76:79], v[70:73], v[34:49]
	ds_read_b128 v[76:79], v81 offset:24576
	v_add_f32_e32 v228, s26, v212
	v_add_f32_e32 v229, s27, v212
	v_add_f32_e32 v230, s28, v212
	v_add_f32_e32 v231, s29, v212
	s_waitcnt lgkmcnt(1)
	v_mfma_f32_32x32x16_bf16 v[34:49], v[252:255], v[66:69], v[34:49]
	ds_read_b128 v[252:255], v80 offset:24576
	v_fma_f32 v216, v110, |v212|, v146
	v_fma_f32 v217, v110, |v217|, v146
	v_fma_f32 v218, v110, |v218|, v146
	v_fma_f32 v219, v110, |v219|, v146
	s_waitcnt lgkmcnt(1)
	v_mfma_f32_32x32x16_bf16 v[18:33], v[76:79], v[70:73], v[18:33]
	ds_read_b128 v[76:79], v81 offset:28672
	v_fma_f32 v220, v110, |v220|, v146
	v_fma_f32 v221, v110, |v221|, v146
	v_fma_f32 v222, v110, |v222|, v146
	v_fma_f32 v223, v110, |v223|, v146
	s_waitcnt lgkmcnt(1)
	v_mfma_f32_32x32x16_bf16 v[18:33], v[252:255], v[66:69], v[18:33]
	ds_read_b128 v[252:255], v80 offset:28672
	v_fma_f32 v224, v110, |v224|, v146
	v_fma_f32 v225, v110, |v225|, v146
	v_fma_f32 v226, v110, |v226|, v146
	v_fma_f32 v227, v110, |v227|, v146
	s_waitcnt lgkmcnt(1)
	v_mfma_f32_32x32x16_bf16 v[2:17], v[76:79], v[70:73], v[2:17]
	v_fma_f32 v228, v110, |v228|, v146
	v_fma_f32 v229, v110, |v229|, v146
	v_fma_f32 v230, v110, |v230|, v146
	v_fma_f32 v231, v110, |v231|, v146
	s_waitcnt lgkmcnt(0)
	v_mfma_f32_32x32x16_bf16 v[2:17], v[252:255], v[66:69], v[2:17]
	v_mov_b32_e32 v66, v126
	s_andn2_b64 exec, exec, s[84:85]
	s_cbranch_execz .LBB0_237
